# phase-1 reduce loads batched; phase-0 GEMV k-loop hand-written with 16 loads in flight (on v7)
# speedup vs baseline: 1.0306x; 1.0123x over previous
; DI void phase1(const Params& p, int wv) {
;     ...
;   for (int idx = blockIdx.x * NTHR + tid_; idx < 4 * 30720; idx += gridDim.x * NTHR) {
;     const int l = idx / 30720, rem = idx % 30720, col = rem % 6144;
;     float s = p.b_mod[l * 6144 + col];
; #pragma unroll
;     for (int kc = 0; kc < 16; ++kc) s += p.modpart[(size_t)(kc * 4 + l) * 30720 + rem];
;     p.mod[idx] = s;
;   }
.LBB0_93:
	s_mov_b32 s8, 0x88888889
	v_mul_hi_i32 v0, v2, s8
	v_add_u32_e32 v0, v0, v2
	v_lshrrev_b32_e32 v3, 31, v0
	v_ashrrev_i32_e32 v0, 14, v0
	v_add_u32_e32 v0, v0, v3
	v_mul_i32_i24_e32 v3, 0x7800, v0
	v_sub_u32_e32 v4, v2, v3
	v_mul_i32_i24_e32 v3, 0x2aab, v4
	v_lshrrev_b32_e32 v5, 31, v3
	v_lshrrev_b32_e32 v3, 26, v3
	v_add_u16_e32 v3, v3, v5
	v_mul_lo_u16_e32 v3, 0x1800, v3
	v_sub_u16_e32 v3, v4, v3
	v_bfe_i32 v3, v3, 0, 16
	s_movk_i32 s8, 0x1800
	v_mad_i32_i24 v6, v0, s8, v3
	v_ashrrev_i32_e32 v7, 31, v6
	v_lshl_add_u64 v[6:7], v[6:7], 2, s[50:51]
	v_ashrrev_i32_e32 v5, 31, v4
	global_load_dword v3, v[6:7], off
	v_lshl_add_u64 v[4:5], v[4:5], 2, s[60:61]
	v_mul_hi_i32_i24_e32 v7, 0x1e000, v0
	v_mul_i32_i24_e32 v6, 0x1e000, v0
	v_lshl_add_u64 v[6:7], v[4:5], 0, v[6:7]
	s_mov_b64 s[10:11], 0x78000
	global_load_dword v40, v[6:7], off
	v_lshl_add_u64 v[6:7], v[6:7], 0, s[10:11]
	global_load_dword v41, v[6:7], off
	v_lshl_add_u64 v[6:7], v[6:7], 0, s[10:11]
	global_load_dword v42, v[6:7], off
	v_lshl_add_u64 v[6:7], v[6:7], 0, s[10:11]
	global_load_dword v43, v[6:7], off
	v_lshl_add_u64 v[6:7], v[6:7], 0, s[10:11]
	global_load_dword v44, v[6:7], off
	v_lshl_add_u64 v[6:7], v[6:7], 0, s[10:11]
	global_load_dword v45, v[6:7], off
	v_lshl_add_u64 v[6:7], v[6:7], 0, s[10:11]
	global_load_dword v46, v[6:7], off
	v_lshl_add_u64 v[6:7], v[6:7], 0, s[10:11]
	global_load_dword v47, v[6:7], off
	v_lshl_add_u64 v[6:7], v[6:7], 0, s[10:11]
	global_load_dword v48, v[6:7], off
	v_lshl_add_u64 v[6:7], v[6:7], 0, s[10:11]
	global_load_dword v49, v[6:7], off
	v_lshl_add_u64 v[6:7], v[6:7], 0, s[10:11]
	global_load_dword v50, v[6:7], off
	v_lshl_add_u64 v[6:7], v[6:7], 0, s[10:11]
	global_load_dword v51, v[6:7], off
	v_lshl_add_u64 v[6:7], v[6:7], 0, s[10:11]
	global_load_dword v52, v[6:7], off
	v_lshl_add_u64 v[6:7], v[6:7], 0, s[10:11]
	global_load_dword v53, v[6:7], off
	v_lshl_add_u64 v[6:7], v[6:7], 0, s[10:11]
	global_load_dword v54, v[6:7], off
	v_lshl_add_u64 v[6:7], v[6:7], 0, s[10:11]
	global_load_dword v55, v[6:7], off
	s_mov_b32 s8, 0x1dfff
	s_waitcnt vmcnt(0)
	v_add_f32_e32 v3, v3, v40
	v_add_f32_e32 v3, v3, v41
	v_add_f32_e32 v3, v3, v42
	v_add_f32_e32 v3, v3, v43
	v_add_f32_e32 v3, v3, v44
	v_add_f32_e32 v3, v3, v45
	v_add_f32_e32 v3, v3, v46
	v_add_f32_e32 v3, v3, v47
	v_add_f32_e32 v3, v3, v48
	v_add_f32_e32 v3, v3, v49
	v_add_f32_e32 v3, v3, v50
	v_add_f32_e32 v3, v3, v51
	v_add_f32_e32 v3, v3, v52
	v_add_f32_e32 v3, v3, v53
	v_add_f32_e32 v3, v3, v54
	v_add_f32_e32 v0, v3, v55
	v_ashrrev_i32_e32 v3, 31, v2
	v_lshl_add_u64 v[4:5], v[2:3], 2, s[62:63]
	v_add_u32_e32 v2, s9, v2
	v_cmp_lt_i32_e32 vcc, s8, v2
	s_or_b64 s[6:7], vcc, s[6:7]
	global_store_dword v[4:5], v0, off
	s_andn2_b64 exec, exec, s[6:7]
	s_cbranch_execnz .LBB0_93

; DI void phase0(const Params& p, char* smem, int wv) {
;     ...
;     const int col = (cg4 * 8 + w) * 256 + lane * 4;
;     const float* wp = p.w_mod + ((size_t)l * DM + kc * 128) * 6144 + col;
;     f32x4 a0 = {0, 0, 0, 0}, a1 = a0, a2 = a0, a3 = a0, a4 = a0;
; #pragma unroll 16
;     for (int k = 0; k < 128; ++k) {
;       const f32x4 wvv = *(const f32x4*)(wp + (size_t)k * 6144);
;       a0 += sf[k] * wvv; a1 += sf[128 + k] * wvv; a2 += sf[256 + k] * wvv; a3 += sf[384 + k] * wvv; a4 += sf[512 + k] * wvv;
;     }
.LBB0_578:
	v_lshl_add_u64 v[36:37], v[32:33], 0, s[2:3]
	s_mov_b64 s[6:7], 0x6000
	global_load_dwordx4 v[68:71], v[36:37], off
	v_lshl_add_u64 v[36:37], v[36:37], 0, s[6:7]
	global_load_dwordx4 v[72:75], v[36:37], off
	v_lshl_add_u64 v[36:37], v[36:37], 0, s[6:7]
	global_load_dwordx4 v[76:79], v[36:37], off
	v_lshl_add_u64 v[36:37], v[36:37], 0, s[6:7]
	global_load_dwordx4 v[80:83], v[36:37], off
	v_lshl_add_u64 v[36:37], v[36:37], 0, s[6:7]
	global_load_dwordx4 v[84:87], v[36:37], off
	v_lshl_add_u64 v[36:37], v[36:37], 0, s[6:7]
	global_load_dwordx4 v[88:91], v[36:37], off
	v_lshl_add_u64 v[36:37], v[36:37], 0, s[6:7]
	global_load_dwordx4 v[92:95], v[36:37], off
	v_lshl_add_u64 v[36:37], v[36:37], 0, s[6:7]
	global_load_dwordx4 v[96:99], v[36:37], off
	v_lshl_add_u64 v[36:37], v[36:37], 0, s[6:7]
	global_load_dwordx4 v[100:103], v[36:37], off
	v_lshl_add_u64 v[36:37], v[36:37], 0, s[6:7]
	global_load_dwordx4 v[104:107], v[36:37], off
	v_lshl_add_u64 v[36:37], v[36:37], 0, s[6:7]
	global_load_dwordx4 v[108:111], v[36:37], off
	v_lshl_add_u64 v[36:37], v[36:37], 0, s[6:7]
	global_load_dwordx4 v[112:115], v[36:37], off
	v_lshl_add_u64 v[36:37], v[36:37], 0, s[6:7]
	global_load_dwordx4 v[116:119], v[36:37], off
	v_lshl_add_u64 v[36:37], v[36:37], 0, s[6:7]
	global_load_dwordx4 v[120:123], v[36:37], off
	v_lshl_add_u64 v[36:37], v[36:37], 0, s[6:7]
	global_load_dwordx4 v[124:127], v[36:37], off
	v_lshl_add_u64 v[36:37], v[36:37], 0, s[6:7]
	global_load_dwordx4 v[128:131], v[36:37], off
	v_mov_b32_e32 v39, s1
	ds_read_b128 v[132:135], v39
	ds_read_b128 v[136:139], v39 offset:16
	ds_read_b128 v[140:143], v39 offset:32
	ds_read_b128 v[144:147], v39 offset:48
	ds_read_b128 v[148:151], v39 offset:512
	ds_read_b128 v[152:155], v39 offset:528
	ds_read_b128 v[156:159], v39 offset:544
	ds_read_b128 v[160:163], v39 offset:560
	ds_read_b128 v[164:167], v39 offset:1024
	ds_read_b128 v[168:171], v39 offset:1040
	ds_read_b128 v[172:175], v39 offset:1056
	ds_read_b128 v[176:179], v39 offset:1072
	ds_read_b128 v[180:183], v39 offset:1536
	ds_read_b128 v[184:187], v39 offset:1552
	ds_read_b128 v[188:191], v39 offset:1568
	ds_read_b128 v[192:195], v39 offset:1584
	ds_read_b128 v[196:199], v39 offset:2048
	ds_read_b128 v[200:203], v39 offset:2064
	ds_read_b128 v[204:207], v39 offset:2080
	ds_read_b128 v[208:211], v39 offset:2096
	s_add_u32 s2, s2, 0x60000
	s_addc_u32 s3, s3, 0
	s_add_i32 s1, s1, 64
	s_cmp_eq_u32 s2, 0x300000
	s_waitcnt lgkmcnt(0)
	s_waitcnt vmcnt(15)
	v_pk_fma_f32 v[14:15], v[68:69], v[132:133], v[14:15] op_sel_hi:[1,0,1]
	v_pk_fma_f32 v[16:17], v[70:71], v[132:133], v[16:17] op_sel_hi:[1,0,1]
	v_pk_fma_f32 v[18:19], v[68:69], v[148:149], v[18:19] op_sel_hi:[1,0,1]
	v_pk_fma_f32 v[20:21], v[70:71], v[148:149], v[20:21] op_sel_hi:[1,0,1]
	v_pk_fma_f32 v[10:11], v[68:69], v[164:165], v[10:11] op_sel_hi:[1,0,1]
	v_pk_fma_f32 v[12:13], v[70:71], v[164:165], v[12:13] op_sel_hi:[1,0,1]
	v_pk_fma_f32 v[6:7], v[68:69], v[180:181], v[6:7] op_sel_hi:[1,0,1]
	v_pk_fma_f32 v[8:9], v[70:71], v[180:181], v[8:9] op_sel_hi:[1,0,1]
	v_pk_fma_f32 v[2:3], v[68:69], v[196:197], v[2:3] op_sel_hi:[1,0,1]
	v_pk_fma_f32 v[4:5], v[70:71], v[196:197], v[4:5] op_sel_hi:[1,0,1]
	s_waitcnt vmcnt(14)
	v_pk_fma_f32 v[14:15], v[72:73], v[132:133], v[14:15] op_sel:[0,1,0]
	v_pk_fma_f32 v[16:17], v[74:75], v[132:133], v[16:17] op_sel:[0,1,0]
	v_pk_fma_f32 v[18:19], v[72:73], v[148:149], v[18:19] op_sel:[0,1,0]
	v_pk_fma_f32 v[20:21], v[74:75], v[148:149], v[20:21] op_sel:[0,1,0]
	v_pk_fma_f32 v[10:11], v[72:73], v[164:165], v[10:11] op_sel:[0,1,0]
	v_pk_fma_f32 v[12:13], v[74:75], v[164:165], v[12:13] op_sel:[0,1,0]
	v_pk_fma_f32 v[6:7], v[72:73], v[180:181], v[6:7] op_sel:[0,1,0]
	v_pk_fma_f32 v[8:9], v[74:75], v[180:181], v[8:9] op_sel:[0,1,0]
	v_pk_fma_f32 v[2:3], v[72:73], v[196:197], v[2:3] op_sel:[0,1,0]
	v_pk_fma_f32 v[4:5], v[74:75], v[196:197], v[4:5] op_sel:[0,1,0]
	s_waitcnt vmcnt(13)
	v_pk_fma_f32 v[14:15], v[76:77], v[134:135], v[14:15] op_sel_hi:[1,0,1]
	v_pk_fma_f32 v[16:17], v[78:79], v[134:135], v[16:17] op_sel_hi:[1,0,1]
	v_pk_fma_f32 v[18:19], v[76:77], v[150:151], v[18:19] op_sel_hi:[1,0,1]
	v_pk_fma_f32 v[20:21], v[78:79], v[150:151], v[20:21] op_sel_hi:[1,0,1]
	v_pk_fma_f32 v[10:11], v[76:77], v[166:167], v[10:11] op_sel_hi:[1,0,1]
	v_pk_fma_f32 v[12:13], v[78:79], v[166:167], v[12:13] op_sel_hi:[1,0,1]
	v_pk_fma_f32 v[6:7], v[76:77], v[182:183], v[6:7] op_sel_hi:[1,0,1]
	v_pk_fma_f32 v[8:9], v[78:79], v[182:183], v[8:9] op_sel_hi:[1,0,1]
	v_pk_fma_f32 v[2:3], v[76:77], v[198:199], v[2:3] op_sel_hi:[1,0,1]
	v_pk_fma_f32 v[4:5], v[78:79], v[198:199], v[4:5] op_sel_hi:[1,0,1]
	s_waitcnt vmcnt(12)
	v_pk_fma_f32 v[14:15], v[80:81], v[134:135], v[14:15] op_sel:[0,1,0]
	v_pk_fma_f32 v[16:17], v[82:83], v[134:135], v[16:17] op_sel:[0,1,0]
	v_pk_fma_f32 v[18:19], v[80:81], v[150:151], v[18:19] op_sel:[0,1,0]
	v_pk_fma_f32 v[20:21], v[82:83], v[150:151], v[20:21] op_sel:[0,1,0]
	v_pk_fma_f32 v[10:11], v[80:81], v[166:167], v[10:11] op_sel:[0,1,0]
	v_pk_fma_f32 v[12:13], v[82:83], v[166:167], v[12:13] op_sel:[0,1,0]
	v_pk_fma_f32 v[6:7], v[80:81], v[182:183], v[6:7] op_sel:[0,1,0]
	v_pk_fma_f32 v[8:9], v[82:83], v[182:183], v[8:9] op_sel:[0,1,0]
	v_pk_fma_f32 v[2:3], v[80:81], v[198:199], v[2:3] op_sel:[0,1,0]
	v_pk_fma_f32 v[4:5], v[82:83], v[198:199], v[4:5] op_sel:[0,1,0]
	s_waitcnt vmcnt(11)
; DI void phase0(const Params& p, char* smem, int wv) {
;     ...
;     for (int k = 0; k < 128; ++k) {
;       const f32x4 wvv = *(const f32x4*)(wp + (size_t)k * 6144);
;       a0 += sf[k] * wvv; a1 += sf[128 + k] * wvv; a2 += sf[256 + k] * wvv; a3 += sf[384 + k] * wvv; a4 += sf[512 + k] * wvv;
;     }
	v_pk_fma_f32 v[14:15], v[84:85], v[136:137], v[14:15] op_sel_hi:[1,0,1]
	v_pk_fma_f32 v[16:17], v[86:87], v[136:137], v[16:17] op_sel_hi:[1,0,1]
	v_pk_fma_f32 v[18:19], v[84:85], v[152:153], v[18:19] op_sel_hi:[1,0,1]
	v_pk_fma_f32 v[20:21], v[86:87], v[152:153], v[20:21] op_sel_hi:[1,0,1]
	v_pk_fma_f32 v[10:11], v[84:85], v[168:169], v[10:11] op_sel_hi:[1,0,1]
	v_pk_fma_f32 v[12:13], v[86:87], v[168:169], v[12:13] op_sel_hi:[1,0,1]
	v_pk_fma_f32 v[6:7], v[84:85], v[184:185], v[6:7] op_sel_hi:[1,0,1]
	v_pk_fma_f32 v[8:9], v[86:87], v[184:185], v[8:9] op_sel_hi:[1,0,1]
	v_pk_fma_f32 v[2:3], v[84:85], v[200:201], v[2:3] op_sel_hi:[1,0,1]
	v_pk_fma_f32 v[4:5], v[86:87], v[200:201], v[4:5] op_sel_hi:[1,0,1]
	s_waitcnt vmcnt(10)
	v_pk_fma_f32 v[14:15], v[88:89], v[136:137], v[14:15] op_sel:[0,1,0]
	v_pk_fma_f32 v[16:17], v[90:91], v[136:137], v[16:17] op_sel:[0,1,0]
	v_pk_fma_f32 v[18:19], v[88:89], v[152:153], v[18:19] op_sel:[0,1,0]
	v_pk_fma_f32 v[20:21], v[90:91], v[152:153], v[20:21] op_sel:[0,1,0]
	v_pk_fma_f32 v[10:11], v[88:89], v[168:169], v[10:11] op_sel:[0,1,0]
	v_pk_fma_f32 v[12:13], v[90:91], v[168:169], v[12:13] op_sel:[0,1,0]
	v_pk_fma_f32 v[6:7], v[88:89], v[184:185], v[6:7] op_sel:[0,1,0]
	v_pk_fma_f32 v[8:9], v[90:91], v[184:185], v[8:9] op_sel:[0,1,0]
	v_pk_fma_f32 v[2:3], v[88:89], v[200:201], v[2:3] op_sel:[0,1,0]
	v_pk_fma_f32 v[4:5], v[90:91], v[200:201], v[4:5] op_sel:[0,1,0]
	s_waitcnt vmcnt(9)
	v_pk_fma_f32 v[14:15], v[92:93], v[138:139], v[14:15] op_sel_hi:[1,0,1]
	v_pk_fma_f32 v[16:17], v[94:95], v[138:139], v[16:17] op_sel_hi:[1,0,1]
	v_pk_fma_f32 v[18:19], v[92:93], v[154:155], v[18:19] op_sel_hi:[1,0,1]
	v_pk_fma_f32 v[20:21], v[94:95], v[154:155], v[20:21] op_sel_hi:[1,0,1]
	v_pk_fma_f32 v[10:11], v[92:93], v[170:171], v[10:11] op_sel_hi:[1,0,1]
	v_pk_fma_f32 v[12:13], v[94:95], v[170:171], v[12:13] op_sel_hi:[1,0,1]
	v_pk_fma_f32 v[6:7], v[92:93], v[186:187], v[6:7] op_sel_hi:[1,0,1]
	v_pk_fma_f32 v[8:9], v[94:95], v[186:187], v[8:9] op_sel_hi:[1,0,1]
	v_pk_fma_f32 v[2:3], v[92:93], v[202:203], v[2:3] op_sel_hi:[1,0,1]
	v_pk_fma_f32 v[4:5], v[94:95], v[202:203], v[4:5] op_sel_hi:[1,0,1]
	s_waitcnt vmcnt(8)
	v_pk_fma_f32 v[14:15], v[96:97], v[138:139], v[14:15] op_sel:[0,1,0]
	v_pk_fma_f32 v[16:17], v[98:99], v[138:139], v[16:17] op_sel:[0,1,0]
	v_pk_fma_f32 v[18:19], v[96:97], v[154:155], v[18:19] op_sel:[0,1,0]
	v_pk_fma_f32 v[20:21], v[98:99], v[154:155], v[20:21] op_sel:[0,1,0]
	v_pk_fma_f32 v[10:11], v[96:97], v[170:171], v[10:11] op_sel:[0,1,0]
	v_pk_fma_f32 v[12:13], v[98:99], v[170:171], v[12:13] op_sel:[0,1,0]
	v_pk_fma_f32 v[6:7], v[96:97], v[186:187], v[6:7] op_sel:[0,1,0]
	v_pk_fma_f32 v[8:9], v[98:99], v[186:187], v[8:9] op_sel:[0,1,0]
	v_pk_fma_f32 v[2:3], v[96:97], v[202:203], v[2:3] op_sel:[0,1,0]
	v_pk_fma_f32 v[4:5], v[98:99], v[202:203], v[4:5] op_sel:[0,1,0]
	s_waitcnt vmcnt(7)
	v_pk_fma_f32 v[14:15], v[100:101], v[140:141], v[14:15] op_sel_hi:[1,0,1]
	v_pk_fma_f32 v[16:17], v[102:103], v[140:141], v[16:17] op_sel_hi:[1,0,1]
	v_pk_fma_f32 v[18:19], v[100:101], v[156:157], v[18:19] op_sel_hi:[1,0,1]
	v_pk_fma_f32 v[20:21], v[102:103], v[156:157], v[20:21] op_sel_hi:[1,0,1]
	v_pk_fma_f32 v[10:11], v[100:101], v[172:173], v[10:11] op_sel_hi:[1,0,1]
	v_pk_fma_f32 v[12:13], v[102:103], v[172:173], v[12:13] op_sel_hi:[1,0,1]
	v_pk_fma_f32 v[6:7], v[100:101], v[188:189], v[6:7] op_sel_hi:[1,0,1]
	v_pk_fma_f32 v[8:9], v[102:103], v[188:189], v[8:9] op_sel_hi:[1,0,1]
	v_pk_fma_f32 v[2:3], v[100:101], v[204:205], v[2:3] op_sel_hi:[1,0,1]
	v_pk_fma_f32 v[4:5], v[102:103], v[204:205], v[4:5] op_sel_hi:[1,0,1]
	s_waitcnt vmcnt(6)
	v_pk_fma_f32 v[14:15], v[104:105], v[140:141], v[14:15] op_sel:[0,1,0]
	v_pk_fma_f32 v[16:17], v[106:107], v[140:141], v[16:17] op_sel:[0,1,0]
	v_pk_fma_f32 v[18:19], v[104:105], v[156:157], v[18:19] op_sel:[0,1,0]
	v_pk_fma_f32 v[20:21], v[106:107], v[156:157], v[20:21] op_sel:[0,1,0]
	v_pk_fma_f32 v[10:11], v[104:105], v[172:173], v[10:11] op_sel:[0,1,0]
	v_pk_fma_f32 v[12:13], v[106:107], v[172:173], v[12:13] op_sel:[0,1,0]
	v_pk_fma_f32 v[6:7], v[104:105], v[188:189], v[6:7] op_sel:[0,1,0]
	v_pk_fma_f32 v[8:9], v[106:107], v[188:189], v[8:9] op_sel:[0,1,0]
	v_pk_fma_f32 v[2:3], v[104:105], v[204:205], v[2:3] op_sel:[0,1,0]
	v_pk_fma_f32 v[4:5], v[106:107], v[204:205], v[4:5] op_sel:[0,1,0]
	s_waitcnt vmcnt(5)
	v_pk_fma_f32 v[14:15], v[108:109], v[142:143], v[14:15] op_sel_hi:[1,0,1]
	v_pk_fma_f32 v[16:17], v[110:111], v[142:143], v[16:17] op_sel_hi:[1,0,1]
	v_pk_fma_f32 v[18:19], v[108:109], v[158:159], v[18:19] op_sel_hi:[1,0,1]
	v_pk_fma_f32 v[20:21], v[110:111], v[158:159], v[20:21] op_sel_hi:[1,0,1]
	v_pk_fma_f32 v[10:11], v[108:109], v[174:175], v[10:11] op_sel_hi:[1,0,1]
	v_pk_fma_f32 v[12:13], v[110:111], v[174:175], v[12:13] op_sel_hi:[1,0,1]
	v_pk_fma_f32 v[6:7], v[108:109], v[190:191], v[6:7] op_sel_hi:[1,0,1]
	v_pk_fma_f32 v[8:9], v[110:111], v[190:191], v[8:9] op_sel_hi:[1,0,1]
	v_pk_fma_f32 v[2:3], v[108:109], v[206:207], v[2:3] op_sel_hi:[1,0,1]
	v_pk_fma_f32 v[4:5], v[110:111], v[206:207], v[4:5] op_sel_hi:[1,0,1]
	s_waitcnt vmcnt(4)
; DI void phase0(const Params& p, char* smem, int wv) {
;     ...
;     for (int k = 0; k < 128; ++k) {
;       const f32x4 wvv = *(const f32x4*)(wp + (size_t)k * 6144);
;       a0 += sf[k] * wvv; a1 += sf[128 + k] * wvv; a2 += sf[256 + k] * wvv; a3 += sf[384 + k] * wvv; a4 += sf[512 + k] * wvv;
;     }
;     float* mp = p.modpart + (size_t)(kc * 4 + l) * 30720 + col;
;     *(f32x4*)(mp) = a0; *(f32x4*)(mp + 6144) = a1; *(f32x4*)(mp + 2 * 6144) = a2;
;     *(f32x4*)(mp + 3 * 6144) = a3; *(f32x4*)(mp + 4 * 6144) = a4;
;     __syncthreads();
	v_pk_fma_f32 v[14:15], v[112:113], v[142:143], v[14:15] op_sel:[0,1,0]
	v_pk_fma_f32 v[16:17], v[114:115], v[142:143], v[16:17] op_sel:[0,1,0]
	v_pk_fma_f32 v[18:19], v[112:113], v[158:159], v[18:19] op_sel:[0,1,0]
	v_pk_fma_f32 v[20:21], v[114:115], v[158:159], v[20:21] op_sel:[0,1,0]
	v_pk_fma_f32 v[10:11], v[112:113], v[174:175], v[10:11] op_sel:[0,1,0]
	v_pk_fma_f32 v[12:13], v[114:115], v[174:175], v[12:13] op_sel:[0,1,0]
	v_pk_fma_f32 v[6:7], v[112:113], v[190:191], v[6:7] op_sel:[0,1,0]
	v_pk_fma_f32 v[8:9], v[114:115], v[190:191], v[8:9] op_sel:[0,1,0]
	v_pk_fma_f32 v[2:3], v[112:113], v[206:207], v[2:3] op_sel:[0,1,0]
	v_pk_fma_f32 v[4:5], v[114:115], v[206:207], v[4:5] op_sel:[0,1,0]
	s_waitcnt vmcnt(3)
	v_pk_fma_f32 v[14:15], v[116:117], v[144:145], v[14:15] op_sel_hi:[1,0,1]
	v_pk_fma_f32 v[16:17], v[118:119], v[144:145], v[16:17] op_sel_hi:[1,0,1]
	v_pk_fma_f32 v[18:19], v[116:117], v[160:161], v[18:19] op_sel_hi:[1,0,1]
	v_pk_fma_f32 v[20:21], v[118:119], v[160:161], v[20:21] op_sel_hi:[1,0,1]
	v_pk_fma_f32 v[10:11], v[116:117], v[176:177], v[10:11] op_sel_hi:[1,0,1]
	v_pk_fma_f32 v[12:13], v[118:119], v[176:177], v[12:13] op_sel_hi:[1,0,1]
	v_pk_fma_f32 v[6:7], v[116:117], v[192:193], v[6:7] op_sel_hi:[1,0,1]
	v_pk_fma_f32 v[8:9], v[118:119], v[192:193], v[8:9] op_sel_hi:[1,0,1]
	v_pk_fma_f32 v[2:3], v[116:117], v[208:209], v[2:3] op_sel_hi:[1,0,1]
	v_pk_fma_f32 v[4:5], v[118:119], v[208:209], v[4:5] op_sel_hi:[1,0,1]
	s_waitcnt vmcnt(2)
	v_pk_fma_f32 v[14:15], v[120:121], v[144:145], v[14:15] op_sel:[0,1,0]
	v_pk_fma_f32 v[16:17], v[122:123], v[144:145], v[16:17] op_sel:[0,1,0]
	v_pk_fma_f32 v[18:19], v[120:121], v[160:161], v[18:19] op_sel:[0,1,0]
	v_pk_fma_f32 v[20:21], v[122:123], v[160:161], v[20:21] op_sel:[0,1,0]
	v_pk_fma_f32 v[10:11], v[120:121], v[176:177], v[10:11] op_sel:[0,1,0]
	v_pk_fma_f32 v[12:13], v[122:123], v[176:177], v[12:13] op_sel:[0,1,0]
	v_pk_fma_f32 v[6:7], v[120:121], v[192:193], v[6:7] op_sel:[0,1,0]
	v_pk_fma_f32 v[8:9], v[122:123], v[192:193], v[8:9] op_sel:[0,1,0]
	v_pk_fma_f32 v[2:3], v[120:121], v[208:209], v[2:3] op_sel:[0,1,0]
	v_pk_fma_f32 v[4:5], v[122:123], v[208:209], v[4:5] op_sel:[0,1,0]
	s_waitcnt vmcnt(1)
	v_pk_fma_f32 v[14:15], v[124:125], v[146:147], v[14:15] op_sel_hi:[1,0,1]
	v_pk_fma_f32 v[16:17], v[126:127], v[146:147], v[16:17] op_sel_hi:[1,0,1]
	v_pk_fma_f32 v[18:19], v[124:125], v[162:163], v[18:19] op_sel_hi:[1,0,1]
	v_pk_fma_f32 v[20:21], v[126:127], v[162:163], v[20:21] op_sel_hi:[1,0,1]
	v_pk_fma_f32 v[10:11], v[124:125], v[178:179], v[10:11] op_sel_hi:[1,0,1]
	v_pk_fma_f32 v[12:13], v[126:127], v[178:179], v[12:13] op_sel_hi:[1,0,1]
	v_pk_fma_f32 v[6:7], v[124:125], v[194:195], v[6:7] op_sel_hi:[1,0,1]
	v_pk_fma_f32 v[8:9], v[126:127], v[194:195], v[8:9] op_sel_hi:[1,0,1]
	v_pk_fma_f32 v[2:3], v[124:125], v[210:211], v[2:3] op_sel_hi:[1,0,1]
	v_pk_fma_f32 v[4:5], v[126:127], v[210:211], v[4:5] op_sel_hi:[1,0,1]
	s_waitcnt vmcnt(0)
	v_pk_fma_f32 v[14:15], v[128:129], v[146:147], v[14:15] op_sel:[0,1,0]
	v_pk_fma_f32 v[16:17], v[130:131], v[146:147], v[16:17] op_sel:[0,1,0]
	v_pk_fma_f32 v[18:19], v[128:129], v[162:163], v[18:19] op_sel:[0,1,0]
	v_pk_fma_f32 v[20:21], v[130:131], v[162:163], v[20:21] op_sel:[0,1,0]
	v_pk_fma_f32 v[10:11], v[128:129], v[178:179], v[10:11] op_sel:[0,1,0]
	v_pk_fma_f32 v[12:13], v[130:131], v[178:179], v[12:13] op_sel:[0,1,0]
	v_pk_fma_f32 v[6:7], v[128:129], v[194:195], v[6:7] op_sel:[0,1,0]
	v_pk_fma_f32 v[8:9], v[130:131], v[194:195], v[8:9] op_sel:[0,1,0]
	v_pk_fma_f32 v[2:3], v[128:129], v[210:211], v[2:3] op_sel:[0,1,0]
	v_pk_fma_f32 v[4:5], v[130:131], v[210:211], v[4:5] op_sel:[0,1,0]
	s_cbranch_scc0 .LBB0_578
	s_lshl_b32 s1, s9, 2
	s_add_i32 s0, s1, s0
	s_mul_hi_i32 s1, s0, 0x1e000
	s_mul_i32 s0, s0, 0x1e000
	s_add_u32 s0, s60, s0
	s_addc_u32 s1, s61, s1
	v_lshl_add_u64 v[22:23], v[30:31], 2, s[0:1]
	global_store_dwordx4 v[22:23], v[14:17], off
	s_add_i32 s8, s8, s80
	s_cmpk_gt_i32 s8, 0xbf
	v_add_co_u32_e32 v14, vcc, s20, v22
	s_nop 1
	v_addc_co_u32_e32 v15, vcc, 0, v23, vcc
	global_store_dwordx4 v[14:15], v[18:21], off
	v_add_co_u32_e32 v14, vcc, 0xc000, v22
	s_nop 1
	v_addc_co_u32_e32 v15, vcc, 0, v23, vcc
	global_store_dwordx4 v[14:15], v[10:13], off
	s_nop 1
	v_add_co_u32_e32 v10, vcc, 0x12000, v22
	s_nop 1
	v_addc_co_u32_e32 v11, vcc, 0, v23, vcc
	global_store_dwordx4 v[10:11], v[6:9], off
	s_nop 1
	v_add_co_u32_e32 v6, vcc, 0x18000, v22
	s_nop 1
	v_addc_co_u32_e32 v7, vcc, 0, v23, vcc
	global_store_dwordx4 v[6:7], v[2:5], off
	s_barrier
	s_cbranch_scc0 .LBB0_574
	v_mov_b32_e32 v2, v0
